# P3 q-up GEMM K-loop deep-pipelined, v_readfirstlane hazard wait added
# speedup vs baseline: 1.0083x; 1.0023x over previous
.LBB0_604:
	v_lshl_add_u64 v[94:95], v[82:83], 0, s[6:7]
	v_lshl_add_u64 v[96:97], v[84:85], 0, s[4:5]
	v_lshl_add_u64 v[98:99], v[86:87], 0, s[4:5]
	v_lshl_add_u64 v[100:101], v[88:89], 0, s[4:5]
	s_mov_b64 s[66:67], 0x5b3c000
	v_lshl_add_u64 v[94:95], v[94:95], 0, s[66:67]
	s_nop 1
	v_readfirstlane_b32 s60, v94
	v_readfirstlane_b32 s61, v95
	v_readfirstlane_b32 s62, v96
	v_readfirstlane_b32 s63, v97
	v_readfirstlane_b32 s64, v102
	v_subrev_u32_e32 v186, s60, v94
	v_subrev_u32_e32 v190, s62, v96
	v_subrev_u32_e32 v191, s62, v98
	v_subrev_u32_e32 v192, s62, v100
	v_add_u32_e32 v187, 0x10800, v186
	v_add_u32_e32 v188, 0x21000, v186
	v_add_u32_e32 v189, 0x31800, v186
	v_add3_u32 v182, v109, v110, v111
	v_add_u32_e32 v183, v109, v112
	v_add3_u32 v184, v113, v110, v111
	v_add_u32_e32 v185, v113, v112
	s_add_u32 s60, s60, 0x80
	s_addc_u32 s61, s61, 0
	s_add_u32 m0, s64, 0x8000
	v_mov_b32_e32 v116, 0
	global_load_lds_dwordx4 v186, s[60:61]
	v_mov_b32_e32 v93, 0
	v_mov_b32_e32 v91, 0
	v_mov_b32_e32 v0, 0
	s_add_u32 m0, s64, 0x9000
	v_mov_b32_e32 v46, 0
	global_load_lds_dwordx4 v187, s[60:61]
	v_mov_b32_e32 v47, 0
	v_mov_b32_e32 v48, 0
	v_mov_b32_e32 v49, 0
	s_add_u32 m0, s64, 0xa000
	v_mov_b32_e32 v38, 0
	global_load_lds_dwordx4 v188, s[60:61]
	v_mov_b32_e32 v39, 0
	v_mov_b32_e32 v40, 0
	v_mov_b32_e32 v41, 0
	s_add_u32 m0, s64, 0xb000
	v_mov_b32_e32 v42, 0
	global_load_lds_dwordx4 v189, s[60:61]
	v_mov_b32_e32 v43, 0
	v_mov_b32_e32 v44, 0
	v_mov_b32_e32 v45, 0
	v_mov_b32_e32 v34, 0
	v_mov_b32_e32 v35, 0
	v_mov_b32_e32 v36, 0
	v_mov_b32_e32 v37, 0
	v_mov_b32_e32 v30, 0
	v_mov_b32_e32 v31, 0
	v_mov_b32_e32 v32, 0
	v_mov_b32_e32 v33, 0
	v_mov_b32_e32 v26, 0
	v_mov_b32_e32 v27, 0
	v_mov_b32_e32 v28, 0
	v_mov_b32_e32 v29, 0
	v_mov_b32_e32 v22, 0
	v_mov_b32_e32 v23, 0
	v_mov_b32_e32 v24, 0
	v_mov_b32_e32 v25, 0
	v_mov_b32_e32 v18, 0
	v_mov_b32_e32 v19, 0
	v_mov_b32_e32 v20, 0
	v_mov_b32_e32 v21, 0
	v_mov_b32_e32 v14, 0
	v_mov_b32_e32 v15, 0
	v_mov_b32_e32 v16, 0
	v_mov_b32_e32 v17, 0
	v_mov_b32_e32 v10, 0
	v_mov_b32_e32 v11, 0
	v_mov_b32_e32 v12, 0
	v_mov_b32_e32 v13, 0
	v_mov_b32_e32 v2, 0
	v_mov_b32_e32 v3, 0
	v_mov_b32_e32 v4, 0
	v_mov_b32_e32 v5, 0
	v_mov_b32_e32 v6, 0
	v_mov_b32_e32 v7, 0
	v_mov_b32_e32 v8, 0
	v_mov_b32_e32 v9, 0
	s_add_u32 s60, s60, 0x80
	s_addc_u32 s61, s61, 0
	s_waitcnt vmcnt(4) lgkmcnt(0)
	s_barrier
	ds_read_b128 v[126:129], v182 offset:0
	ds_read_b128 v[142:145], v183 offset:16384
	ds_read_b128 v[146:149], v183 offset:18432
	ds_read_b128 v[130:133], v182 offset:2048
	ds_read_b128 v[150:153], v183 offset:20480
	ds_read_b128 v[134:137], v182 offset:4096
	ds_read_b128 v[138:141], v182 offset:6144
	s_mov_b32 s65, 5
.Lp3q_loop:
	ds_read_b128 v[154:157], v184 offset:0
	ds_read_b128 v[170:173], v185 offset:16384
	ds_read_b128 v[174:177], v185 offset:18432
	ds_read_b128 v[158:161], v184 offset:2048
	ds_read_b128 v[178:181], v185 offset:20480
	ds_read_b128 v[162:165], v184 offset:4096
	ds_read_b128 v[166:169], v184 offset:6144
	s_waitcnt lgkmcnt(7)
	s_add_u32 m0, s64, 0xc000
	v_mfma_f32_16x16x32_bf16 v[46:49], v[126:129], v[142:145], v[46:49]
	v_dot2c_f32_bf16_e32 v116, v126, v126
	v_mfma_f32_16x16x32_bf16 v[38:41], v[126:129], v[146:149], v[38:41]
	v_dot2c_f32_bf16_e32 v93, v130, v130
	global_load_lds_dwordx4 v190, s[62:63]
	v_mfma_f32_16x16x32_bf16 v[42:45], v[126:129], v[150:153], v[42:45]
	v_dot2c_f32_bf16_e32 v91, v134, v134
	v_dot2c_f32_bf16_e32 v0, v138, v138
	v_mfma_f32_16x16x32_bf16 v[34:37], v[130:133], v[142:145], v[34:37]
	v_dot2c_f32_bf16_e32 v116, v126, v126
	s_add_u32 m0, s64, 0xd000
	v_mfma_f32_16x16x32_bf16 v[30:33], v[130:133], v[146:149], v[30:33]
	v_dot2c_f32_bf16_e32 v93, v130, v130
	v_mfma_f32_16x16x32_bf16 v[26:29], v[130:133], v[150:153], v[26:29]
	v_dot2c_f32_bf16_e32 v91, v134, v134
	global_load_lds_dwordx4 v191, s[62:63]
	v_dot2c_f32_bf16_e32 v0, v138, v138
	v_mfma_f32_16x16x32_bf16 v[22:25], v[134:137], v[142:145], v[22:25]
	v_dot2c_f32_bf16_e32 v116, v126, v126
	v_mfma_f32_16x16x32_bf16 v[18:21], v[134:137], v[146:149], v[18:21]
	v_dot2c_f32_bf16_e32 v93, v130, v130
	s_add_u32 m0, s64, 0xe000
	v_mfma_f32_16x16x32_bf16 v[14:17], v[134:137], v[150:153], v[14:17]
	v_dot2c_f32_bf16_e32 v91, v134, v134
	v_dot2c_f32_bf16_e32 v0, v138, v138
	v_mfma_f32_16x16x32_bf16 v[10:13], v[138:141], v[142:145], v[10:13]
	v_dot2c_f32_bf16_e32 v116, v126, v126
	global_load_lds_dwordx4 v192, s[62:63]
	v_mfma_f32_16x16x32_bf16 v[2:5], v[138:141], v[146:149], v[2:5]
	v_dot2c_f32_bf16_e32 v93, v130, v130
	v_mfma_f32_16x16x32_bf16 v[6:9], v[138:141], v[150:153], v[6:9]
	v_dot2c_f32_bf16_e32 v91, v134, v134
	v_dot2c_f32_bf16_e32 v0, v138, v138
	s_add_u32 s62, s62, 0x80
	s_addc_u32 s63, s63, 0
	s_waitcnt lgkmcnt(0)
	s_barrier
	s_add_u32 m0, s64, 0x0
	v_mfma_f32_16x16x32_bf16 v[46:49], v[154:157], v[170:173], v[46:49]
	v_dot2c_f32_bf16_e32 v116, v154, v154
	v_mfma_f32_16x16x32_bf16 v[38:41], v[154:157], v[174:177], v[38:41]
	global_load_lds_dwordx4 v186, s[60:61]
	v_dot2c_f32_bf16_e32 v93, v158, v158
	v_mfma_f32_16x16x32_bf16 v[42:45], v[154:157], v[178:181], v[42:45]
	v_dot2c_f32_bf16_e32 v91, v162, v162
	v_dot2c_f32_bf16_e32 v0, v166, v166
	s_add_u32 m0, s64, 0x1000
	v_mfma_f32_16x16x32_bf16 v[34:37], v[158:161], v[170:173], v[34:37]
	v_dot2c_f32_bf16_e32 v116, v154, v154
	v_mfma_f32_16x16x32_bf16 v[30:33], v[158:161], v[174:177], v[30:33]
	global_load_lds_dwordx4 v187, s[60:61]
	v_dot2c_f32_bf16_e32 v93, v158, v158
	v_mfma_f32_16x16x32_bf16 v[26:29], v[158:161], v[178:181], v[26:29]
	v_dot2c_f32_bf16_e32 v91, v162, v162
	v_dot2c_f32_bf16_e32 v0, v166, v166
	s_waitcnt vmcnt(2)
	s_barrier
	ds_read_b128 v[126:129], v182 offset:32768
	ds_read_b128 v[142:145], v183 offset:49152
	ds_read_b128 v[146:149], v183 offset:51200
	ds_read_b128 v[130:133], v182 offset:34816
	ds_read_b128 v[150:153], v183 offset:53248
	ds_read_b128 v[134:137], v182 offset:36864
	ds_read_b128 v[138:141], v182 offset:38912
	s_add_u32 m0, s64, 0x2000
	v_mfma_f32_16x16x32_bf16 v[22:25], v[162:165], v[170:173], v[22:25]
	v_dot2c_f32_bf16_e32 v116, v154, v154
	v_mfma_f32_16x16x32_bf16 v[18:21], v[162:165], v[174:177], v[18:21]
	global_load_lds_dwordx4 v188, s[60:61]
	v_dot2c_f32_bf16_e32 v93, v158, v158
	v_mfma_f32_16x16x32_bf16 v[14:17], v[162:165], v[178:181], v[14:17]
	v_dot2c_f32_bf16_e32 v91, v162, v162
	v_dot2c_f32_bf16_e32 v0, v166, v166
	s_add_u32 m0, s64, 0x3000
	v_mfma_f32_16x16x32_bf16 v[10:13], v[166:169], v[170:173], v[10:13]
	v_dot2c_f32_bf16_e32 v116, v154, v154
	v_mfma_f32_16x16x32_bf16 v[2:5], v[166:169], v[174:177], v[2:5]
	global_load_lds_dwordx4 v189, s[60:61]
	v_dot2c_f32_bf16_e32 v93, v158, v158
	v_mfma_f32_16x16x32_bf16 v[6:9], v[166:169], v[178:181], v[6:9]
	v_dot2c_f32_bf16_e32 v91, v162, v162
	v_dot2c_f32_bf16_e32 v0, v166, v166
	s_add_u32 s60, s60, 0x80
	s_addc_u32 s61, s61, 0
	ds_read_b128 v[154:157], v184 offset:32768
	ds_read_b128 v[170:173], v185 offset:49152
	ds_read_b128 v[174:177], v185 offset:51200
	ds_read_b128 v[158:161], v184 offset:34816
	ds_read_b128 v[178:181], v185 offset:53248
	ds_read_b128 v[162:165], v184 offset:36864
	ds_read_b128 v[166:169], v184 offset:38912
	s_waitcnt lgkmcnt(7)
	s_add_u32 m0, s64, 0x4000
	v_mfma_f32_16x16x32_bf16 v[46:49], v[126:129], v[142:145], v[46:49]
	v_dot2c_f32_bf16_e32 v116, v126, v126
	v_mfma_f32_16x16x32_bf16 v[38:41], v[126:129], v[146:149], v[38:41]
	v_dot2c_f32_bf16_e32 v93, v130, v130
	global_load_lds_dwordx4 v190, s[62:63]
	v_mfma_f32_16x16x32_bf16 v[42:45], v[126:129], v[150:153], v[42:45]
	v_dot2c_f32_bf16_e32 v91, v134, v134
	v_dot2c_f32_bf16_e32 v0, v138, v138
	v_mfma_f32_16x16x32_bf16 v[34:37], v[130:133], v[142:145], v[34:37]
	v_dot2c_f32_bf16_e32 v116, v126, v126
	s_add_u32 m0, s64, 0x5000
	v_mfma_f32_16x16x32_bf16 v[30:33], v[130:133], v[146:149], v[30:33]
	v_dot2c_f32_bf16_e32 v93, v130, v130
	v_mfma_f32_16x16x32_bf16 v[26:29], v[130:133], v[150:153], v[26:29]
	v_dot2c_f32_bf16_e32 v91, v134, v134
	global_load_lds_dwordx4 v191, s[62:63]
	v_dot2c_f32_bf16_e32 v0, v138, v138
	v_mfma_f32_16x16x32_bf16 v[22:25], v[134:137], v[142:145], v[22:25]
	v_dot2c_f32_bf16_e32 v116, v126, v126
	v_mfma_f32_16x16x32_bf16 v[18:21], v[134:137], v[146:149], v[18:21]
	v_dot2c_f32_bf16_e32 v93, v130, v130
	s_add_u32 m0, s64, 0x6000
	v_mfma_f32_16x16x32_bf16 v[14:17], v[134:137], v[150:153], v[14:17]
	v_dot2c_f32_bf16_e32 v91, v134, v134
	v_dot2c_f32_bf16_e32 v0, v138, v138
	v_mfma_f32_16x16x32_bf16 v[10:13], v[138:141], v[142:145], v[10:13]
	v_dot2c_f32_bf16_e32 v116, v126, v126
	global_load_lds_dwordx4 v192, s[62:63]
	v_mfma_f32_16x16x32_bf16 v[2:5], v[138:141], v[146:149], v[2:5]
	v_dot2c_f32_bf16_e32 v93, v130, v130
	v_mfma_f32_16x16x32_bf16 v[6:9], v[138:141], v[150:153], v[6:9]
	v_dot2c_f32_bf16_e32 v91, v134, v134
	v_dot2c_f32_bf16_e32 v0, v138, v138
	s_add_u32 s62, s62, 0x80
	s_addc_u32 s63, s63, 0
	s_waitcnt lgkmcnt(0)
	s_barrier
	s_add_u32 m0, s64, 0x8000
	v_mfma_f32_16x16x32_bf16 v[46:49], v[154:157], v[170:173], v[46:49]
	v_dot2c_f32_bf16_e32 v116, v154, v154
	v_mfma_f32_16x16x32_bf16 v[38:41], v[154:157], v[174:177], v[38:41]
	global_load_lds_dwordx4 v186, s[60:61]
	v_dot2c_f32_bf16_e32 v93, v158, v158
	v_mfma_f32_16x16x32_bf16 v[42:45], v[154:157], v[178:181], v[42:45]
	v_dot2c_f32_bf16_e32 v91, v162, v162
	v_dot2c_f32_bf16_e32 v0, v166, v166
	s_add_u32 m0, s64, 0x9000
	v_mfma_f32_16x16x32_bf16 v[34:37], v[158:161], v[170:173], v[34:37]
	v_dot2c_f32_bf16_e32 v116, v154, v154
	v_mfma_f32_16x16x32_bf16 v[30:33], v[158:161], v[174:177], v[30:33]
	global_load_lds_dwordx4 v187, s[60:61]
	v_dot2c_f32_bf16_e32 v93, v158, v158
	v_mfma_f32_16x16x32_bf16 v[26:29], v[158:161], v[178:181], v[26:29]
	v_dot2c_f32_bf16_e32 v91, v162, v162
	v_dot2c_f32_bf16_e32 v0, v166, v166
	s_waitcnt vmcnt(2)
	s_barrier
	ds_read_b128 v[126:129], v182 offset:0
	ds_read_b128 v[142:145], v183 offset:16384
	ds_read_b128 v[146:149], v183 offset:18432
	ds_read_b128 v[130:133], v182 offset:2048
	ds_read_b128 v[150:153], v183 offset:20480
	ds_read_b128 v[134:137], v182 offset:4096
	ds_read_b128 v[138:141], v182 offset:6144
	s_add_u32 m0, s64, 0xa000
	v_mfma_f32_16x16x32_bf16 v[22:25], v[162:165], v[170:173], v[22:25]
	v_dot2c_f32_bf16_e32 v116, v154, v154
	v_mfma_f32_16x16x32_bf16 v[18:21], v[162:165], v[174:177], v[18:21]
	global_load_lds_dwordx4 v188, s[60:61]
	v_dot2c_f32_bf16_e32 v93, v158, v158
	v_mfma_f32_16x16x32_bf16 v[14:17], v[162:165], v[178:181], v[14:17]
	v_dot2c_f32_bf16_e32 v91, v162, v162
	v_dot2c_f32_bf16_e32 v0, v166, v166
	s_add_u32 m0, s64, 0xb000
	v_mfma_f32_16x16x32_bf16 v[10:13], v[166:169], v[170:173], v[10:13]
	v_dot2c_f32_bf16_e32 v116, v154, v154
	v_mfma_f32_16x16x32_bf16 v[2:5], v[166:169], v[174:177], v[2:5]
	global_load_lds_dwordx4 v189, s[60:61]
	v_dot2c_f32_bf16_e32 v93, v158, v158
	v_mfma_f32_16x16x32_bf16 v[6:9], v[166:169], v[178:181], v[6:9]
	v_dot2c_f32_bf16_e32 v91, v162, v162
	v_dot2c_f32_bf16_e32 v0, v166, v166
	s_add_u32 s60, s60, 0x80
	s_addc_u32 s61, s61, 0
	s_sub_i32 s65, s65, 1
	s_cmp_lg_u32 s65, 0
	s_cbranch_scc1 .Lp3q_loop
	ds_read_b128 v[154:157], v184 offset:0
	ds_read_b128 v[170:173], v185 offset:16384
	ds_read_b128 v[174:177], v185 offset:18432
	ds_read_b128 v[158:161], v184 offset:2048
	ds_read_b128 v[178:181], v185 offset:20480
	ds_read_b128 v[162:165], v184 offset:4096
	ds_read_b128 v[166:169], v184 offset:6144
	s_waitcnt lgkmcnt(7)
	s_add_u32 m0, s64, 0xc000
	v_mfma_f32_16x16x32_bf16 v[46:49], v[126:129], v[142:145], v[46:49]
	v_dot2c_f32_bf16_e32 v116, v126, v126
	v_mfma_f32_16x16x32_bf16 v[38:41], v[126:129], v[146:149], v[38:41]
	v_dot2c_f32_bf16_e32 v93, v130, v130
	global_load_lds_dwordx4 v190, s[62:63]
	v_mfma_f32_16x16x32_bf16 v[42:45], v[126:129], v[150:153], v[42:45]
	v_dot2c_f32_bf16_e32 v91, v134, v134
	v_dot2c_f32_bf16_e32 v0, v138, v138
	v_mfma_f32_16x16x32_bf16 v[34:37], v[130:133], v[142:145], v[34:37]
	v_dot2c_f32_bf16_e32 v116, v126, v126
	s_add_u32 m0, s64, 0xd000
	v_mfma_f32_16x16x32_bf16 v[30:33], v[130:133], v[146:149], v[30:33]
	v_dot2c_f32_bf16_e32 v93, v130, v130
	v_mfma_f32_16x16x32_bf16 v[26:29], v[130:133], v[150:153], v[26:29]
	v_dot2c_f32_bf16_e32 v91, v134, v134
	global_load_lds_dwordx4 v191, s[62:63]
	v_dot2c_f32_bf16_e32 v0, v138, v138
	v_mfma_f32_16x16x32_bf16 v[22:25], v[134:137], v[142:145], v[22:25]
	v_dot2c_f32_bf16_e32 v116, v126, v126
	v_mfma_f32_16x16x32_bf16 v[18:21], v[134:137], v[146:149], v[18:21]
	v_dot2c_f32_bf16_e32 v93, v130, v130
	s_add_u32 m0, s64, 0xe000
	v_mfma_f32_16x16x32_bf16 v[14:17], v[134:137], v[150:153], v[14:17]
	v_dot2c_f32_bf16_e32 v91, v134, v134
	v_dot2c_f32_bf16_e32 v0, v138, v138
	v_mfma_f32_16x16x32_bf16 v[10:13], v[138:141], v[142:145], v[10:13]
	v_dot2c_f32_bf16_e32 v116, v126, v126
	global_load_lds_dwordx4 v192, s[62:63]
	v_mfma_f32_16x16x32_bf16 v[2:5], v[138:141], v[146:149], v[2:5]
	v_dot2c_f32_bf16_e32 v93, v130, v130
	v_mfma_f32_16x16x32_bf16 v[6:9], v[138:141], v[150:153], v[6:9]
	v_dot2c_f32_bf16_e32 v91, v134, v134
	v_dot2c_f32_bf16_e32 v0, v138, v138
	s_add_u32 s62, s62, 0x80
	s_addc_u32 s63, s63, 0
	s_waitcnt lgkmcnt(0)
	s_barrier
	v_mfma_f32_16x16x32_bf16 v[46:49], v[154:157], v[170:173], v[46:49]
	v_dot2c_f32_bf16_e32 v116, v154, v154
	v_mfma_f32_16x16x32_bf16 v[38:41], v[154:157], v[174:177], v[38:41]
	v_dot2c_f32_bf16_e32 v93, v158, v158
	v_mfma_f32_16x16x32_bf16 v[42:45], v[154:157], v[178:181], v[42:45]
	v_dot2c_f32_bf16_e32 v91, v162, v162
	v_dot2c_f32_bf16_e32 v0, v166, v166
	v_mfma_f32_16x16x32_bf16 v[34:37], v[158:161], v[170:173], v[34:37]
	v_dot2c_f32_bf16_e32 v116, v154, v154
	v_mfma_f32_16x16x32_bf16 v[30:33], v[158:161], v[174:177], v[30:33]
	v_dot2c_f32_bf16_e32 v93, v158, v158
	v_mfma_f32_16x16x32_bf16 v[26:29], v[158:161], v[178:181], v[26:29]
	v_dot2c_f32_bf16_e32 v91, v162, v162
	v_dot2c_f32_bf16_e32 v0, v166, v166
	s_waitcnt vmcnt(0)
	s_barrier
	ds_read_b128 v[126:129], v182 offset:32768
	ds_read_b128 v[142:145], v183 offset:49152
	ds_read_b128 v[146:149], v183 offset:51200
	ds_read_b128 v[130:133], v182 offset:34816
	ds_read_b128 v[150:153], v183 offset:53248
	ds_read_b128 v[134:137], v182 offset:36864
	ds_read_b128 v[138:141], v182 offset:38912
	v_mfma_f32_16x16x32_bf16 v[22:25], v[162:165], v[170:173], v[22:25]
	v_dot2c_f32_bf16_e32 v116, v154, v154
	v_mfma_f32_16x16x32_bf16 v[18:21], v[162:165], v[174:177], v[18:21]
	v_dot2c_f32_bf16_e32 v93, v158, v158
	v_mfma_f32_16x16x32_bf16 v[14:17], v[162:165], v[178:181], v[14:17]
	v_dot2c_f32_bf16_e32 v91, v162, v162
	v_dot2c_f32_bf16_e32 v0, v166, v166
	v_mfma_f32_16x16x32_bf16 v[10:13], v[166:169], v[170:173], v[10:13]
	v_dot2c_f32_bf16_e32 v116, v154, v154
	v_mfma_f32_16x16x32_bf16 v[2:5], v[166:169], v[174:177], v[2:5]
	v_dot2c_f32_bf16_e32 v93, v158, v158
	v_mfma_f32_16x16x32_bf16 v[6:9], v[166:169], v[178:181], v[6:9]
	v_dot2c_f32_bf16_e32 v91, v162, v162
	v_dot2c_f32_bf16_e32 v0, v166, v166
	ds_read_b128 v[154:157], v184 offset:32768
	ds_read_b128 v[170:173], v185 offset:49152
	ds_read_b128 v[174:177], v185 offset:51200
	ds_read_b128 v[158:161], v184 offset:34816
	ds_read_b128 v[178:181], v185 offset:53248
	ds_read_b128 v[162:165], v184 offset:36864
	ds_read_b128 v[166:169], v184 offset:38912
	s_waitcnt lgkmcnt(7)
	v_mfma_f32_16x16x32_bf16 v[46:49], v[126:129], v[142:145], v[46:49]
	v_dot2c_f32_bf16_e32 v116, v126, v126
	v_mfma_f32_16x16x32_bf16 v[38:41], v[126:129], v[146:149], v[38:41]
	v_dot2c_f32_bf16_e32 v93, v130, v130
	v_mfma_f32_16x16x32_bf16 v[42:45], v[126:129], v[150:153], v[42:45]
	v_dot2c_f32_bf16_e32 v91, v134, v134
	v_dot2c_f32_bf16_e32 v0, v138, v138
	v_mfma_f32_16x16x32_bf16 v[34:37], v[130:133], v[142:145], v[34:37]
	v_dot2c_f32_bf16_e32 v116, v126, v126
	v_mfma_f32_16x16x32_bf16 v[30:33], v[130:133], v[146:149], v[30:33]
	v_dot2c_f32_bf16_e32 v93, v130, v130
	v_mfma_f32_16x16x32_bf16 v[26:29], v[130:133], v[150:153], v[26:29]
	v_dot2c_f32_bf16_e32 v91, v134, v134
	v_dot2c_f32_bf16_e32 v0, v138, v138
	v_mfma_f32_16x16x32_bf16 v[22:25], v[134:137], v[142:145], v[22:25]
	v_dot2c_f32_bf16_e32 v116, v126, v126
	v_mfma_f32_16x16x32_bf16 v[18:21], v[134:137], v[146:149], v[18:21]
	v_dot2c_f32_bf16_e32 v93, v130, v130
	v_mfma_f32_16x16x32_bf16 v[14:17], v[134:137], v[150:153], v[14:17]
	v_dot2c_f32_bf16_e32 v91, v134, v134
	v_dot2c_f32_bf16_e32 v0, v138, v138
	v_mfma_f32_16x16x32_bf16 v[10:13], v[138:141], v[142:145], v[10:13]
	v_dot2c_f32_bf16_e32 v116, v126, v126
	v_mfma_f32_16x16x32_bf16 v[2:5], v[138:141], v[146:149], v[2:5]
	v_dot2c_f32_bf16_e32 v93, v130, v130
	v_mfma_f32_16x16x32_bf16 v[6:9], v[138:141], v[150:153], v[6:9]
	v_dot2c_f32_bf16_e32 v91, v134, v134
	v_dot2c_f32_bf16_e32 v0, v138, v138
	s_waitcnt lgkmcnt(0)
	s_barrier
	v_mfma_f32_16x16x32_bf16 v[46:49], v[154:157], v[170:173], v[46:49]
	v_dot2c_f32_bf16_e32 v116, v154, v154
	v_mfma_f32_16x16x32_bf16 v[38:41], v[154:157], v[174:177], v[38:41]
	v_dot2c_f32_bf16_e32 v93, v158, v158
	v_mfma_f32_16x16x32_bf16 v[42:45], v[154:157], v[178:181], v[42:45]
	v_dot2c_f32_bf16_e32 v91, v162, v162
	v_dot2c_f32_bf16_e32 v0, v166, v166
	v_mfma_f32_16x16x32_bf16 v[34:37], v[158:161], v[170:173], v[34:37]
	v_dot2c_f32_bf16_e32 v116, v154, v154
	v_mfma_f32_16x16x32_bf16 v[30:33], v[158:161], v[174:177], v[30:33]
	v_dot2c_f32_bf16_e32 v93, v158, v158
	v_mfma_f32_16x16x32_bf16 v[26:29], v[158:161], v[178:181], v[26:29]
	v_dot2c_f32_bf16_e32 v91, v162, v162
	v_dot2c_f32_bf16_e32 v0, v166, v166
	v_mfma_f32_16x16x32_bf16 v[22:25], v[162:165], v[170:173], v[22:25]
	v_dot2c_f32_bf16_e32 v116, v154, v154
	v_mfma_f32_16x16x32_bf16 v[18:21], v[162:165], v[174:177], v[18:21]
	v_dot2c_f32_bf16_e32 v93, v158, v158
	v_mfma_f32_16x16x32_bf16 v[14:17], v[162:165], v[178:181], v[14:17]
	v_dot2c_f32_bf16_e32 v91, v162, v162
	v_dot2c_f32_bf16_e32 v0, v166, v166
	v_mfma_f32_16x16x32_bf16 v[10:13], v[166:169], v[170:173], v[10:13]
	v_dot2c_f32_bf16_e32 v116, v154, v154
	v_mfma_f32_16x16x32_bf16 v[2:5], v[166:169], v[174:177], v[2:5]
	v_dot2c_f32_bf16_e32 v93, v158, v158
	v_mfma_f32_16x16x32_bf16 v[6:9], v[166:169], v[178:181], v[6:9]
	v_dot2c_f32_bf16_e32 v91, v162, v162
	v_dot2c_f32_bf16_e32 v0, v166, v166
	s_nop 7
